# window-attention boundary tiles: per-score mask (add, sub, max_i32, cmp, cndmask) replaced by one unsigned range check (add, cmp into rotating SGPR pairs, cndmask)
# speedup vs baseline: 1.0104x; 1.0104x over previous
.LBB0_185:
	v_cndmask_b32_e64 v32, 0, 1, s[40:41]
	v_cmp_ne_u32_e64 s[0:1], 1, v32
	s_and_saveexec_b64 s[40:41], s[68:69]
	s_cbranch_execz .LBB0_192
	v_add_u32_e32 v40, v122, v116
	ds_read_b128 v[32:35], v40
	ds_read_b128 v[98:101], v40 offset:32
	ds_read_b128 v[36:39], v40 offset:4608
	ds_read_b128 v[102:105], v40 offset:4640
	ds_read_b128 v[106:109], v40 offset:64
	ds_read_b128 v[110:113], v40 offset:96
	ds_read_b128 v[126:129], v40 offset:4672
	ds_read_b128 v[130:133], v40 offset:4704
	s_setprio 1
	s_setprio 0
	s_waitcnt lgkmcnt(7)
	v_mfma_f32_32x32x16_bf16 v[48:63], v[32:35], v[64:67], 0
	s_waitcnt lgkmcnt(5)
	v_mfma_f32_32x32x16_bf16 v[32:47], v[36:39], v[64:67], 0
	v_mfma_f32_32x32x16_bf16 v[48:63], v[98:101], v[68:71], v[48:63]
	s_waitcnt lgkmcnt(4)
	v_mfma_f32_32x32x16_bf16 v[32:47], v[102:105], v[68:71], v[32:47]
	s_waitcnt lgkmcnt(3)
	v_mfma_f32_32x32x16_bf16 v[48:63], v[106:109], v[72:75], v[48:63]
	s_waitcnt lgkmcnt(1)
	v_mfma_f32_32x32x16_bf16 v[32:47], v[126:129], v[72:75], v[32:47]
	v_add_u32_e32 v126, v123, v116
	v_mfma_f32_32x32x16_bf16 v[48:63], v[110:113], v[76:79], v[48:63]
	ds_read_b128 v[110:113], v126 offset:9216
	ds_read_b128 v[106:109], v126 offset:9248
	ds_read_b128 v[102:105], v126 offset:9280
	ds_read_b128 v[98:101], v126 offset:9312
	s_waitcnt lgkmcnt(4)
	v_mfma_f32_32x32x16_bf16 v[32:47], v[130:133], v[76:79], v[32:47]
	s_and_b64 vcc, exec, s[0:1]
	s_cbranch_vccnz .LBB0_188
	s_add_i32 s10, s27, -1
	v_add_u32_e32 v156, s10, v124
	s_lshl_b32 s11, s27, 1
	s_add_i32 s11, s11, -1
	v_add_u32_e32 v96, 0x77, v156
	v_add_u32_e32 v127, 0x57, v156
	v_add_u32_e32 v128, 0x76, v156
	v_cmp_gt_u32_e64 s[4:5], s11, v96
	v_cmp_gt_u32_e64 s[6:7], s11, v127
	v_cmp_gt_u32_e64 s[8:9], s11, v128
	v_cndmask_b32_e64 v48, v212, v48, s[4:5]
	v_cndmask_b32_e64 v32, v212, v32, s[6:7]
	v_cndmask_b32_e64 v49, v212, v49, s[8:9]
	v_add_u32_e32 v96, 0x56, v156
	v_add_u32_e32 v127, 0x75, v156
	v_add_u32_e32 v128, 0x55, v156
	v_cmp_gt_u32_e64 s[4:5], s11, v96
	v_cmp_gt_u32_e64 s[6:7], s11, v127
	v_cmp_gt_u32_e64 s[8:9], s11, v128
	v_cndmask_b32_e64 v33, v212, v33, s[4:5]
	v_cndmask_b32_e64 v50, v212, v50, s[6:7]
	v_cndmask_b32_e64 v34, v212, v34, s[8:9]
	v_add_u32_e32 v96, 0x74, v156
	v_add_u32_e32 v127, 0x54, v156
	v_add_u32_e32 v128, 0x73, v156
	v_cmp_gt_u32_e64 s[4:5], s11, v96
	v_cmp_gt_u32_e64 s[6:7], s11, v127
	v_cmp_gt_u32_e64 s[8:9], s11, v128
	v_cndmask_b32_e64 v51, v212, v51, s[4:5]
	v_cndmask_b32_e64 v35, v212, v35, s[6:7]
	v_cndmask_b32_e64 v52, v212, v52, s[8:9]
	v_add_u32_e32 v96, 0x53, v156
	v_add_u32_e32 v127, 0x72, v156
	v_add_u32_e32 v128, 0x52, v156
	v_cmp_gt_u32_e64 s[4:5], s11, v96
	v_cmp_gt_u32_e64 s[6:7], s11, v127
	v_cmp_gt_u32_e64 s[8:9], s11, v128
	v_cndmask_b32_e64 v36, v212, v36, s[4:5]
	v_cndmask_b32_e64 v53, v212, v53, s[6:7]
	v_cndmask_b32_e64 v37, v212, v37, s[8:9]
	v_add_u32_e32 v96, 0x71, v156
	v_add_u32_e32 v127, 0x51, v156
	v_add_u32_e32 v128, 0x70, v156
	v_cmp_gt_u32_e64 s[4:5], s11, v96
	v_cmp_gt_u32_e64 s[6:7], s11, v127
	v_cmp_gt_u32_e64 s[8:9], s11, v128
	v_cndmask_b32_e64 v54, v212, v54, s[4:5]
	v_cndmask_b32_e64 v38, v212, v38, s[6:7]
	v_cndmask_b32_e64 v55, v212, v55, s[8:9]
	v_add_u32_e32 v96, 0x50, v156
	v_add_u32_e32 v127, 0x67, v156
	v_add_u32_e32 v128, 0x47, v156
	v_cmp_gt_u32_e64 s[4:5], s11, v96
	v_cmp_gt_u32_e64 s[6:7], s11, v127
	v_cmp_gt_u32_e64 s[8:9], s11, v128
	v_cndmask_b32_e64 v39, v212, v39, s[4:5]
	v_cndmask_b32_e64 v56, v212, v56, s[6:7]
	v_cndmask_b32_e64 v40, v212, v40, s[8:9]
	v_add_u32_e32 v96, 0x66, v156
	v_add_u32_e32 v127, 0x46, v156
	v_add_u32_e32 v128, 0x65, v156
	v_cmp_gt_u32_e64 s[4:5], s11, v96
	v_cmp_gt_u32_e64 s[6:7], s11, v127
	v_cmp_gt_u32_e64 s[8:9], s11, v128
	v_cndmask_b32_e64 v57, v212, v57, s[4:5]
	v_cndmask_b32_e64 v41, v212, v41, s[6:7]
	v_cndmask_b32_e64 v58, v212, v58, s[8:9]
	v_add_u32_e32 v96, 0x45, v156
	v_add_u32_e32 v127, 0x64, v156
	v_add_u32_e32 v128, 0x44, v156
	v_cmp_gt_u32_e64 s[4:5], s11, v96
	v_cmp_gt_u32_e64 s[6:7], s11, v127
	v_cmp_gt_u32_e64 s[8:9], s11, v128
	v_cndmask_b32_e64 v42, v212, v42, s[4:5]
	v_cndmask_b32_e64 v59, v212, v59, s[6:7]
	v_cndmask_b32_e64 v43, v212, v43, s[8:9]
	v_add_u32_e32 v96, 0x63, v156
	v_add_u32_e32 v127, 0x43, v156
	v_add_u32_e32 v128, 0x62, v156
	v_cmp_gt_u32_e64 s[4:5], s11, v96
	v_cmp_gt_u32_e64 s[6:7], s11, v127
	v_cmp_gt_u32_e64 s[8:9], s11, v128
	v_cndmask_b32_e64 v60, v212, v60, s[4:5]
	v_cndmask_b32_e64 v44, v212, v44, s[6:7]
	v_cndmask_b32_e64 v61, v212, v61, s[8:9]
	v_add_u32_e32 v96, 0x42, v156
	v_add_u32_e32 v127, 0x61, v156
	v_add_u32_e32 v128, 0x41, v156
	v_cmp_gt_u32_e64 s[4:5], s11, v96
	v_cmp_gt_u32_e64 s[6:7], s11, v127
	v_cmp_gt_u32_e64 s[8:9], s11, v128
	v_cndmask_b32_e64 v45, v212, v45, s[4:5]
	v_cndmask_b32_e64 v62, v212, v62, s[6:7]
	v_cndmask_b32_e64 v46, v212, v46, s[8:9]
	v_add_u32_e32 v96, 0x60, v156
	v_add_u32_e32 v127, 64, v156
	v_cmp_gt_u32_e64 s[4:5], s11, v96
	v_cmp_gt_u32_e64 s[6:7], s11, v127
	s_nop 0
	v_cndmask_b32_e64 v63, v212, v63, s[4:5]
	v_cndmask_b32_e64 v47, v212, v47, s[6:7]

.LBB0_202:
	v_add_u32_e32 v40, v122, v116
	ds_read_b128 v[32:35], v40 offset:18432
	ds_read_b128 v[98:101], v40 offset:18464
	ds_read_b128 v[36:39], v40 offset:23040
	ds_read_b128 v[102:105], v40 offset:23072
	ds_read_b128 v[106:109], v40 offset:18496
	ds_read_b128 v[110:113], v40 offset:18528
	ds_read_b128 v[126:129], v40 offset:23104
	ds_read_b128 v[130:133], v40 offset:23136
	s_setprio 1
	s_setprio 0
	s_waitcnt lgkmcnt(7)
	v_mfma_f32_32x32x16_bf16 v[48:63], v[32:35], v[64:67], 0
	s_waitcnt lgkmcnt(5)
	v_mfma_f32_32x32x16_bf16 v[32:47], v[36:39], v[64:67], 0
	v_mfma_f32_32x32x16_bf16 v[48:63], v[98:101], v[68:71], v[48:63]
	s_waitcnt lgkmcnt(4)
	v_mfma_f32_32x32x16_bf16 v[32:47], v[102:105], v[68:71], v[32:47]
	s_waitcnt lgkmcnt(3)
	v_mfma_f32_32x32x16_bf16 v[48:63], v[106:109], v[72:75], v[48:63]
	s_waitcnt lgkmcnt(1)
	v_mfma_f32_32x32x16_bf16 v[32:47], v[126:129], v[72:75], v[32:47]
	v_add_u32_e32 v126, v123, v116
	v_mfma_f32_32x32x16_bf16 v[48:63], v[110:113], v[76:79], v[48:63]
	ds_read_b128 v[110:113], v126 offset:27648
	ds_read_b128 v[106:109], v126 offset:27680
	ds_read_b128 v[102:105], v126 offset:27712
	ds_read_b128 v[98:101], v126 offset:27744
	s_waitcnt lgkmcnt(4)
	v_mfma_f32_32x32x16_bf16 v[32:47], v[130:133], v[76:79], v[32:47]
	s_and_b64 vcc, exec, s[0:1]
	s_cbranch_vccnz .LBB0_204
	s_add_i32 s10, s27, -1
	v_add_u32_e32 v156, s10, v124
	s_lshl_b32 s11, s27, 1
	s_add_i32 s11, s11, -1
	v_add_u32_e32 v96, 55, v156
	v_add_u32_e32 v127, 23, v156
	v_add_u32_e32 v128, 54, v156
	v_cmp_gt_u32_e64 s[4:5], s11, v96
	v_cmp_gt_u32_e64 s[6:7], s11, v127
	v_cmp_gt_u32_e64 s[8:9], s11, v128
	v_cndmask_b32_e64 v48, v212, v48, s[4:5]
	v_cndmask_b32_e64 v32, v212, v32, s[6:7]
	v_cndmask_b32_e64 v49, v212, v49, s[8:9]
	v_add_u32_e32 v96, 22, v156
	v_add_u32_e32 v127, 53, v156
	v_add_u32_e32 v128, 21, v156
	v_cmp_gt_u32_e64 s[4:5], s11, v96
	v_cmp_gt_u32_e64 s[6:7], s11, v127
	v_cmp_gt_u32_e64 s[8:9], s11, v128
	v_cndmask_b32_e64 v33, v212, v33, s[4:5]
	v_cndmask_b32_e64 v50, v212, v50, s[6:7]
	v_cndmask_b32_e64 v34, v212, v34, s[8:9]
	v_add_u32_e32 v96, 52, v156
	v_add_u32_e32 v127, 20, v156
	v_add_u32_e32 v128, 51, v156
	v_cmp_gt_u32_e64 s[4:5], s11, v96
	v_cmp_gt_u32_e64 s[6:7], s11, v127
	v_cmp_gt_u32_e64 s[8:9], s11, v128
	v_cndmask_b32_e64 v51, v212, v51, s[4:5]
	v_cndmask_b32_e64 v35, v212, v35, s[6:7]
	v_cndmask_b32_e64 v52, v212, v52, s[8:9]
	v_add_u32_e32 v96, 19, v156
	v_add_u32_e32 v127, 50, v156
	v_add_u32_e32 v128, 18, v156
	v_cmp_gt_u32_e64 s[4:5], s11, v96
	v_cmp_gt_u32_e64 s[6:7], s11, v127
	v_cmp_gt_u32_e64 s[8:9], s11, v128
	v_cndmask_b32_e64 v36, v212, v36, s[4:5]
	v_cndmask_b32_e64 v53, v212, v53, s[6:7]
	v_cndmask_b32_e64 v37, v212, v37, s[8:9]
	v_add_u32_e32 v96, 49, v156
	v_add_u32_e32 v127, 17, v156
	v_add_u32_e32 v128, 48, v156
	v_cmp_gt_u32_e64 s[4:5], s11, v96
	v_cmp_gt_u32_e64 s[6:7], s11, v127
	v_cmp_gt_u32_e64 s[8:9], s11, v128
	v_cndmask_b32_e64 v54, v212, v54, s[4:5]
	v_cndmask_b32_e64 v38, v212, v38, s[6:7]
	v_cndmask_b32_e64 v55, v212, v55, s[8:9]
	v_add_u32_e32 v96, 16, v156
	v_add_u32_e32 v127, 39, v156
	v_add_u32_e32 v128, 7, v156
	v_cmp_gt_u32_e64 s[4:5], s11, v96
	v_cmp_gt_u32_e64 s[6:7], s11, v127
	v_cmp_gt_u32_e64 s[8:9], s11, v128
	v_cndmask_b32_e64 v39, v212, v39, s[4:5]
	v_cndmask_b32_e64 v56, v212, v56, s[6:7]
	v_cndmask_b32_e64 v40, v212, v40, s[8:9]
	v_add_u32_e32 v96, 38, v156
	v_add_u32_e32 v127, 6, v156
	v_add_u32_e32 v128, 37, v156
	v_cmp_gt_u32_e64 s[4:5], s11, v96
	v_cmp_gt_u32_e64 s[6:7], s11, v127
	v_cmp_gt_u32_e64 s[8:9], s11, v128
	v_cndmask_b32_e64 v57, v212, v57, s[4:5]
	v_cndmask_b32_e64 v41, v212, v41, s[6:7]
	v_cndmask_b32_e64 v58, v212, v58, s[8:9]
	v_add_u32_e32 v96, 5, v156
	v_add_u32_e32 v127, 36, v156
	v_add_u32_e32 v128, 4, v156
	v_cmp_gt_u32_e64 s[4:5], s11, v96
	v_cmp_gt_u32_e64 s[6:7], s11, v127
	v_cmp_gt_u32_e64 s[8:9], s11, v128
	v_cndmask_b32_e64 v42, v212, v42, s[4:5]
	v_cndmask_b32_e64 v59, v212, v59, s[6:7]
	v_cndmask_b32_e64 v43, v212, v43, s[8:9]
	v_add_u32_e32 v96, 35, v156
	v_add_u32_e32 v127, 3, v156
	v_add_u32_e32 v128, 34, v156
	v_cmp_gt_u32_e64 s[4:5], s11, v96
	v_cmp_gt_u32_e64 s[6:7], s11, v127
	v_cmp_gt_u32_e64 s[8:9], s11, v128
	v_cndmask_b32_e64 v60, v212, v60, s[4:5]
	v_cndmask_b32_e64 v44, v212, v44, s[6:7]
	v_cndmask_b32_e64 v61, v212, v61, s[8:9]
	v_add_u32_e32 v96, 2, v156
	v_add_u32_e32 v127, 33, v156
	v_add_u32_e32 v128, 1, v156
	v_cmp_gt_u32_e64 s[4:5], s11, v96
	v_cmp_gt_u32_e64 s[6:7], s11, v127
	v_cmp_gt_u32_e64 s[8:9], s11, v128
	v_cndmask_b32_e64 v45, v212, v45, s[4:5]
	v_cndmask_b32_e64 v62, v212, v62, s[6:7]
	v_cndmask_b32_e64 v46, v212, v46, s[8:9]
	v_add_u32_e32 v96, 32, v156
	v_add_u32_e32 v127, 0, v156
	v_cmp_gt_u32_e64 s[4:5], s11, v96
	v_cmp_gt_u32_e64 s[6:7], s11, v127
	s_nop 0
	v_cndmask_b32_e64 v63, v212, v63, s[4:5]
	v_cndmask_b32_e64 v47, v212, v47, s[6:7]
